# in-proj and gate/up GEMM epilogues: the eight rs[row] loads issued together, one wait, per-group vmcnt(0) drains removed; temporaries renamed off registers that pending stores still read
# speedup vs baseline: 1.0171x; 1.0057x over previous
; __device__ __forceinline__ unsigned cvt_pk_bf16(float lo, float hi) { f32x2c_t v = {lo, hi}; bf16x2c_t b = __builtin_convertvector(v, bf16x2c_t); return __builtin_bit_cast(unsigned, b); }
;     __device__ __forceinline__ void operator()(const f32x4 (&acc)[2][2][4][2], const Unit& u, int wr, int wc, int fr, int fq) const {
;         const float sc0 = (u.pn >= 3 && u.pn < 6) ? 0.08838834764831845f : ((u.pn >= 12 && u.pn < 15) ? 0.125f * 1.4426950408889634f : 1.f);
;         const int row0 = u.pm * BM + wr * 64 + fr, col0 = u.pn * BM + wc * 32 + 8 * fq;
; #pragma unroll
;         for (int ai = 0; ai < 2; ++ai)
; #pragma unroll
;             for (int m = 0; m < 4; ++m) { bf16_t* rowp = O + (size_t)(row0 + ai * HALF + m * 16) * ldc + col0; const float sc = sc0 * rs[row0 + ai * HALF + m * 16];
; #pragma unroll
;                 for (int bj = 0; bj < 2; ++bj) { const f32x4 v0 = acc[ai][bj][m][0] * sc, v1 = acc[ai][bj][m][1] * sc;
;                     u32x4 w; w.x = cvt_pk_bf16(v0[0], v0[1]); w.y = cvt_pk_bf16(v0[2], v0[3]); w.z = cvt_pk_bf16(v1[0], v1[1]); w.w = cvt_pk_bf16(v1[2], v1[3]);
;                     *(u32x4*)(rowp + bj * HALF) = w; } }
.LBB0_141:
	v_lshl_add_u32 v140, s83, 8, v148
	v_ashrrev_i32_e32 v141, 31, v140
	v_lshl_add_u64 v[144:145], v[140:141], 2, s[40:41]
	global_load_dword v164, v[144:145], off
	global_load_dword v166, v[144:145], off offset:64
	global_load_dword v168, v[144:145], off offset:128
	global_load_dword v170, v[144:145], off offset:192
	global_load_dword v172, v[144:145], off offset:512
	global_load_dword v174, v[144:145], off offset:576
	global_load_dword v176, v[144:145], off offset:640
	global_load_dword v178, v[144:145], off offset:704
	s_add_i32 s34, s82, -3
	s_add_i32 s22, s82, -12
	s_cmp_lt_u32 s22, 3
	s_cselect_b64 vcc, -1, 0
	s_cmp_gt_u32 s34, 2
	v_cndmask_b32_e32 v156, 1.0, v225, vcc
	s_cselect_b64 vcc, -1, 0
	v_lshl_or_b32 v146, s82, 8, v150
	v_cndmask_b32_e32 v162, v230, v156, vcc
	v_mov_b64_e32 v[142:143], s[36:37]
	v_ashrrev_i32_e32 v147, 31, v146
	v_mad_i64_i32 v[152:153], s[22:23], v140, s61, v[142:143]
	v_or_b32_e32 v154, 16, v140
	v_lshlrev_b64 v[146:147], 1, v[146:147]
	v_ashrrev_i32_e32 v155, 31, v154
	v_lshl_add_u64 v[152:153], v[152:153], 0, v[146:147]
	v_lshl_add_u64 v[156:157], v[154:155], 2, s[40:41]
	s_andn2_b64 vcc, exec, s[38:39]
	s_mov_b64 s[34:35], -1
	s_waitcnt vmcnt(0)
	v_mov_b32_e32 v141, v164
	v_mul_f32_e32 v158, v162, v141
	v_pk_mul_f32 v[128:129], v[128:129], v[158:159] op_sel_hi:[1,0]
	v_pk_mul_f32 v[126:127], v[126:127], v[158:159] op_sel_hi:[1,0]
	v_pk_mul_f32 v[124:125], v[124:125], v[158:159] op_sel_hi:[1,0]
	v_pk_mul_f32 v[122:123], v[122:123], v[158:159] op_sel_hi:[1,0]
	v_pk_mul_f32 v[120:121], v[120:121], v[158:159] op_sel_hi:[1,0]
	v_pk_mul_f32 v[118:119], v[118:119], v[158:159] op_sel_hi:[1,0]
	v_pk_mul_f32 v[160:161], v[116:117], v[158:159] op_sel_hi:[1,0]
	v_pk_mul_f32 v[158:159], v[114:115], v[158:159] op_sel_hi:[1,0]
	v_cvt_pk_bf16_f32 v114, v126, v127
	v_cvt_pk_bf16_f32 v115, v128, v129
	v_cvt_pk_bf16_f32 v116, v122, v123
	v_cvt_pk_bf16_f32 v117, v124, v125
	v_cvt_pk_bf16_f32 v118, v118, v119
	v_cvt_pk_bf16_f32 v119, v120, v121
	v_cvt_pk_bf16_f32 v120, v158, v159
	v_cvt_pk_bf16_f32 v121, v160, v161
	global_store_dwordx4 v[152:153], v[114:117], off
	global_store_dwordx4 v[152:153], v[118:121], off offset:256
	v_or_b32_e32 v180, 32, v140
	v_mad_i64_i32 v[182:183], s[22:23], v154, s61, v[142:143]
	v_ashrrev_i32_e32 v181, 31, v180
	v_lshl_add_u64 v[182:183], v[182:183], 0, v[146:147]
	v_lshl_add_u64 v[184:185], v[180:181], 2, s[40:41]
	v_mov_b32_e32 v186, v166
	v_mul_f32_e32 v186, v162, v186
	v_pk_mul_f32 v[112:113], v[112:113], v[186:187] op_sel_hi:[1,0]
	v_pk_mul_f32 v[110:111], v[110:111], v[186:187] op_sel_hi:[1,0]
	v_pk_mul_f32 v[108:109], v[108:109], v[186:187] op_sel_hi:[1,0]
	v_pk_mul_f32 v[106:107], v[106:107], v[186:187] op_sel_hi:[1,0]
	v_pk_mul_f32 v[104:105], v[104:105], v[186:187] op_sel_hi:[1,0]
	v_pk_mul_f32 v[102:103], v[102:103], v[186:187] op_sel_hi:[1,0]
	v_pk_mul_f32 v[122:123], v[100:101], v[186:187] op_sel_hi:[1,0]
	v_pk_mul_f32 v[186:187], v[98:99], v[186:187] op_sel_hi:[1,0]
	v_cvt_pk_bf16_f32 v98, v110, v111
	v_cvt_pk_bf16_f32 v99, v112, v113
	v_cvt_pk_bf16_f32 v100, v106, v107
	v_cvt_pk_bf16_f32 v101, v108, v109
	v_cvt_pk_bf16_f32 v102, v102, v103
	v_cvt_pk_bf16_f32 v103, v104, v105
	v_cvt_pk_bf16_f32 v104, v186, v187
	v_cvt_pk_bf16_f32 v105, v122, v123
	global_store_dwordx4 v[182:183], v[98:101], off
	global_store_dwordx4 v[182:183], v[102:105], off offset:256
	v_or_b32_e32 v122, 48, v140
	v_mad_i64_i32 v[124:125], s[22:23], v180, s61, v[142:143]
	v_ashrrev_i32_e32 v123, 31, v122
	v_lshl_add_u64 v[124:125], v[124:125], 0, v[146:147]
	v_lshl_add_u64 v[126:127], v[122:123], 2, s[40:41]
	v_mov_b32_e32 v128, v168
	v_mul_f32_e32 v128, v162, v128
	v_pk_mul_f32 v[96:97], v[96:97], v[128:129] op_sel_hi:[1,0]
	v_pk_mul_f32 v[94:95], v[94:95], v[128:129] op_sel_hi:[1,0]
	v_pk_mul_f32 v[92:93], v[92:93], v[128:129] op_sel_hi:[1,0]
	v_pk_mul_f32 v[90:91], v[90:91], v[128:129] op_sel_hi:[1,0]
	v_pk_mul_f32 v[84:85], v[84:85], v[128:129] op_sel_hi:[1,0]
	v_pk_mul_f32 v[82:83], v[82:83], v[128:129] op_sel_hi:[1,0]
	v_pk_mul_f32 v[106:107], v[76:77], v[128:129] op_sel_hi:[1,0]
	v_pk_mul_f32 v[128:129], v[74:75], v[128:129] op_sel_hi:[1,0]
	v_cvt_pk_bf16_f32 v74, v94, v95
	v_cvt_pk_bf16_f32 v75, v96, v97
	v_cvt_pk_bf16_f32 v76, v90, v91
	v_cvt_pk_bf16_f32 v77, v92, v93
	v_cvt_pk_bf16_f32 v82, v82, v83
	v_cvt_pk_bf16_f32 v83, v84, v85
	v_cvt_pk_bf16_f32 v84, v128, v129
	v_cvt_pk_bf16_f32 v85, v106, v107
	global_store_dwordx4 v[124:125], v[74:77], off
	global_store_dwordx4 v[124:125], v[82:85], off offset:256
	v_mad_i64_i32 v[188:189], s[22:23], v122, s61, v[142:143]
	v_lshl_add_u64 v[188:189], v[188:189], 0, v[146:147]
	v_mov_b32_e32 v190, v170
	v_mul_f32_e32 v190, v162, v190
	v_pk_mul_f32 v[196:197], v[88:89], v[190:191] op_sel_hi:[1,0]
	v_pk_mul_f32 v[198:199], v[86:87], v[190:191] op_sel_hi:[1,0]
	v_pk_mul_f32 v[80:81], v[80:81], v[190:191] op_sel_hi:[1,0]
; __device__ __forceinline__ unsigned cvt_pk_bf16(float lo, float hi) { f32x2c_t v = {lo, hi}; bf16x2c_t b = __builtin_convertvector(v, bf16x2c_t); return __builtin_bit_cast(unsigned, b); }
; #define PG8_BAR __builtin_amdgcn_s_barrier()
;     __device__ __forceinline__ void operator()(const f32x4 (&acc)[2][2][4][2], const Unit& u, int wr, int wc, int fr, int fq) const {
;     ...
;         for (int ai = 0; ai < 2; ++ai)
; #pragma unroll
;             for (int m = 0; m < 4; ++m) { bf16_t* rowp = O + (size_t)(row0 + ai * HALF + m * 16) * ldc + col0; const float sc = sc0 * rs[row0 + ai * HALF + m * 16];
; #pragma unroll
;                 for (int bj = 0; bj < 2; ++bj) { const f32x4 v0 = acc[ai][bj][m][0] * sc, v1 = acc[ai][bj][m][1] * sc;
;                     u32x4 w; w.x = cvt_pk_bf16(v0[0], v0[1]); w.y = cvt_pk_bf16(v0[2], v0[3]); w.z = cvt_pk_bf16(v1[0], v1[1]); w.w = cvt_pk_bf16(v1[2], v1[3]);
;                     *(u32x4*)(rowp + bj * HALF) = w; } }
; template <class Epi, class Sched, bool ALIGN_EPI = false, bool SP2 = false>
; __device__ __forceinline__ void gemm_phase(PG8_LAS unsigned char* lds, const Gemm g, const Sched& S, const Epi& E) {
;     ...
;         if constexpr (ALIGN_EPI) { if (wr == 0) PG8_BAR; }
;         if constexpr (!Epi::AFTER_DRAIN) { E(acc, cur, wr, wc, fr, fq); S.done(cur); }
;         if (!has_next) break;
; #pragma unroll
;         for (int a = 0; a < 2; ++a)
; #pragma unroll
;             for (int b = 0; b < 2; ++b)
; #pragma unroll
;                 for (int m = 0; m < 4; ++m)
; #pragma unroll
;                     for (int n = 0; n < 2; ++n) acc[a][b][m][n] = (f32x4){0.f, 0.f, 0.f, 0.f};
;         cur = nxt; cA = nA; cB = nB; ++ui;
;         if constexpr (ALIGN_EPI) { if (wr == 1) PG8_BAR; }
;     }
	v_pk_mul_f32 v[78:79], v[78:79], v[190:191] op_sel_hi:[1,0]
	v_pk_mul_f32 v[72:73], v[72:73], v[190:191] op_sel_hi:[1,0]
	v_pk_mul_f32 v[70:71], v[70:71], v[190:191] op_sel_hi:[1,0]
	v_pk_mul_f32 v[86:87], v[68:69], v[190:191] op_sel_hi:[1,0]
	v_pk_mul_f32 v[190:191], v[66:67], v[190:191] op_sel_hi:[1,0]
	v_cvt_pk_bf16_f32 v66, v198, v199
	v_cvt_pk_bf16_f32 v67, v196, v197
	v_cvt_pk_bf16_f32 v68, v78, v79
	v_cvt_pk_bf16_f32 v69, v80, v81
	v_cvt_pk_bf16_f32 v70, v70, v71
	v_cvt_pk_bf16_f32 v71, v72, v73
	v_cvt_pk_bf16_f32 v72, v190, v191
	v_cvt_pk_bf16_f32 v73, v86, v87
	global_store_dwordx4 v[188:189], v[66:69], off
	global_store_dwordx4 v[188:189], v[70:73], off offset:256
	v_add_u32_e32 v86, 0x80, v140
	v_mad_i64_i32 v[86:87], s[22:23], v86, s61, v[142:143]
	v_lshl_add_u64 v[86:87], v[86:87], 0, v[146:147]
	v_mov_b32_e32 v88, v172
	v_mul_f32_e32 v88, v162, v88
	v_pk_mul_f32 v[64:65], v[64:65], v[88:89] op_sel_hi:[1,0]
	v_pk_mul_f32 v[62:63], v[62:63], v[88:89] op_sel_hi:[1,0]
	v_pk_mul_f32 v[60:61], v[60:61], v[88:89] op_sel_hi:[1,0]
	v_pk_mul_f32 v[58:59], v[58:59], v[88:89] op_sel_hi:[1,0]
	v_pk_mul_f32 v[56:57], v[56:57], v[88:89] op_sel_hi:[1,0]
	v_pk_mul_f32 v[54:55], v[54:55], v[88:89] op_sel_hi:[1,0]
	v_pk_mul_f32 v[90:91], v[48:49], v[88:89] op_sel_hi:[1,0]
	v_pk_mul_f32 v[88:89], v[46:47], v[88:89] op_sel_hi:[1,0]
	v_cvt_pk_bf16_f32 v46, v62, v63
	v_cvt_pk_bf16_f32 v47, v64, v65
	v_cvt_pk_bf16_f32 v48, v58, v59
	v_cvt_pk_bf16_f32 v49, v60, v61
	v_cvt_pk_bf16_f32 v54, v54, v55
	v_cvt_pk_bf16_f32 v55, v56, v57
	v_cvt_pk_bf16_f32 v56, v88, v89
	v_cvt_pk_bf16_f32 v57, v90, v91
	global_store_dwordx4 v[86:87], v[46:49], off
	global_store_dwordx4 v[86:87], v[54:57], off offset:256
	v_add_u32_e32 v152, 0x90, v140
	v_mad_i64_i32 v[152:153], s[22:23], v152, s61, v[142:143]
	v_lshl_add_u64 v[152:153], v[152:153], 0, v[146:147]
	v_mov_b32_e32 v154, v174
	v_mul_f32_e32 v154, v162, v154
	v_pk_mul_f32 v[52:53], v[52:53], v[154:155] op_sel_hi:[1,0]
	v_pk_mul_f32 v[50:51], v[50:51], v[154:155] op_sel_hi:[1,0]
	v_pk_mul_f32 v[44:45], v[44:45], v[154:155] op_sel_hi:[1,0]
	v_pk_mul_f32 v[42:43], v[42:43], v[154:155] op_sel_hi:[1,0]
	v_pk_mul_f32 v[40:41], v[40:41], v[154:155] op_sel_hi:[1,0]
	v_pk_mul_f32 v[38:39], v[38:39], v[154:155] op_sel_hi:[1,0]
	v_pk_mul_f32 v[160:161], v[32:33], v[154:155] op_sel_hi:[1,0]
	v_pk_mul_f32 v[154:155], v[30:31], v[154:155] op_sel_hi:[1,0]
	v_cvt_pk_bf16_f32 v30, v50, v51
	v_cvt_pk_bf16_f32 v31, v52, v53
	v_cvt_pk_bf16_f32 v32, v42, v43
	v_cvt_pk_bf16_f32 v33, v44, v45
	v_cvt_pk_bf16_f32 v38, v38, v39
	v_cvt_pk_bf16_f32 v39, v40, v41
	v_cvt_pk_bf16_f32 v40, v154, v155
	v_cvt_pk_bf16_f32 v41, v160, v161
	global_store_dwordx4 v[152:153], v[30:33], off
	global_store_dwordx4 v[152:153], v[38:41], off offset:256
	v_add_u32_e32 v42, 0xa0, v140
	v_mad_i64_i32 v[42:43], s[22:23], v42, s61, v[142:143]
	v_lshl_add_u64 v[42:43], v[42:43], 0, v[146:147]
	v_mov_b32_e32 v44, v176
	v_mul_f32_e32 v44, v162, v44
	v_pk_mul_f32 v[36:37], v[36:37], v[44:45] op_sel_hi:[1,0]
	v_pk_mul_f32 v[34:35], v[34:35], v[44:45] op_sel_hi:[1,0]
	v_pk_mul_f32 v[28:29], v[28:29], v[44:45] op_sel_hi:[1,0]
	v_pk_mul_f32 v[26:27], v[26:27], v[44:45] op_sel_hi:[1,0]
	v_pk_mul_f32 v[24:25], v[24:25], v[44:45] op_sel_hi:[1,0]
	v_pk_mul_f32 v[22:23], v[22:23], v[44:45] op_sel_hi:[1,0]
	v_pk_mul_f32 v[50:51], v[20:21], v[44:45] op_sel_hi:[1,0]
	v_pk_mul_f32 v[44:45], v[18:19], v[44:45] op_sel_hi:[1,0]
	v_cvt_pk_bf16_f32 v18, v34, v35
	v_cvt_pk_bf16_f32 v19, v36, v37
	v_cvt_pk_bf16_f32 v20, v26, v27
	v_cvt_pk_bf16_f32 v21, v28, v29
	v_cvt_pk_bf16_f32 v22, v22, v23
	v_cvt_pk_bf16_f32 v23, v24, v25
	v_cvt_pk_bf16_f32 v24, v44, v45
	v_cvt_pk_bf16_f32 v25, v50, v51
	global_store_dwordx4 v[42:43], v[18:21], off
	global_store_dwordx4 v[42:43], v[22:25], off offset:256
	v_add_u32_e32 v58, 0xb0, v140
	v_mad_i64_i32 v[58:59], s[22:23], v58, s61, v[142:143]
	v_lshl_add_u64 v[58:59], v[58:59], 0, v[146:147]
	v_mov_b32_e32 v60, v178
	v_mul_f32_e32 v60, v162, v60
	v_pk_mul_f32 v[16:17], v[16:17], v[60:61] op_sel_hi:[1,0]
	v_pk_mul_f32 v[14:15], v[14:15], v[60:61] op_sel_hi:[1,0]
	v_pk_mul_f32 v[12:13], v[12:13], v[60:61] op_sel_hi:[1,0]
	v_pk_mul_f32 v[10:11], v[10:11], v[60:61] op_sel_hi:[1,0]
	v_pk_mul_f32 v[8:9], v[8:9], v[60:61] op_sel_hi:[1,0]
	v_pk_mul_f32 v[6:7], v[6:7], v[60:61] op_sel_hi:[1,0]
	v_pk_mul_f32 v[62:63], v[4:5], v[60:61] op_sel_hi:[1,0]
	v_pk_mul_f32 v[60:61], v[2:3], v[60:61] op_sel_hi:[1,0]
	v_cvt_pk_bf16_f32 v2, v14, v15
	v_cvt_pk_bf16_f32 v3, v16, v17
	v_cvt_pk_bf16_f32 v4, v10, v11
	v_cvt_pk_bf16_f32 v5, v12, v13
	v_cvt_pk_bf16_f32 v6, v6, v7
	v_cvt_pk_bf16_f32 v7, v8, v9
	v_cvt_pk_bf16_f32 v8, v60, v61
	v_cvt_pk_bf16_f32 v9, v62, v63
	global_store_dwordx4 v[58:59], v[2:5], off
	global_store_dwordx4 v[58:59], v[6:9], off offset:256
	s_cbranch_vccnz .LBB0_134
	s_andn2_b64 vcc, exec, s[26:27]
	s_cbranch_vccnz .LBB0_133
	s_barrier
	s_branch .LBB0_133

; __device__ __forceinline__ unsigned cvt_pk_bf16(float lo, float hi) { f32x2c_t v = {lo, hi}; bf16x2c_t b = __builtin_convertvector(v, bf16x2c_t); return __builtin_bit_cast(unsigned, b); }
;     __device__ __forceinline__ static float sw(float g, float u) { return g * __builtin_amdgcn_rcpf(1.f + __builtin_amdgcn_exp2f(-1.4426950408889634f * g)) * u; }
;     __device__ __forceinline__ void operator()(const f32x4 (&acc)[2][2][4][2], const Unit& u, int wr, int wc, int fr, int fq) const {
;         const int row0 = u.pm * BM + wr * 64 + fr, col0 = u.pn * HALF + wc * 32 + 8 * fq;
; #pragma unroll
;         for (int ai = 0; ai < 2; ++ai)
; #pragma unroll
;             for (int m = 0; m < 4; ++m) { bf16_t* rowp = O + (size_t)(row0 + ai * HALF + m * 16) * ldc + col0;
;                 const float r_ = rs[row0 + ai * HALF + m * 16];
;                 const f32x4 g0 = acc[ai][0][m][0] * r_, g1 = acc[ai][0][m][1] * r_, u0 = acc[ai][1][m][0] * r_, u1 = acc[ai][1][m][1] * r_;
;                 u32x4 w; w.x = cvt_pk_bf16(sw(g0[0], u0[0]), sw(g0[1], u0[1])); w.y = cvt_pk_bf16(sw(g0[2], u0[2]), sw(g0[3], u0[3]));
;                 w.z = cvt_pk_bf16(sw(g1[0], u1[0]), sw(g1[1], u1[1])); w.w = cvt_pk_bf16(sw(g1[2], u1[2]), sw(g1[3], u1[3]));
;                 *(u32x4*)rowp = w; }
.LBB0_707:
	v_lshl_or_b32 v144, s82, 7, v150
	v_lshl_add_u32 v140, s83, 8, v148
	v_ashrrev_i32_e32 v145, 31, v144
	v_mov_b64_e32 v[142:143], s[36:37]
	v_ashrrev_i32_e32 v141, 31, v140
	v_mad_i64_i32 v[146:147], s[22:23], v140, s73, v[142:143]
	v_lshlrev_b64 v[144:145], 1, v[144:145]
	v_lshl_add_u64 v[152:153], v[146:147], 0, v[144:145]
	v_lshl_add_u64 v[146:147], v[140:141], 2, s[42:43]
	global_load_dword v164, v[146:147], off
	global_load_dword v166, v[146:147], off offset:64
	global_load_dword v168, v[146:147], off offset:128
	global_load_dword v170, v[146:147], off offset:192
	global_load_dword v172, v[146:147], off offset:512
	global_load_dword v174, v[146:147], off offset:576
	global_load_dword v176, v[146:147], off offset:640
	global_load_dword v178, v[146:147], off offset:704
	s_mov_b64 s[34:35], -1
	s_andn2_b64 vcc, exec, s[40:41]
	v_readlane_b32 s91, v255, 54
	s_waitcnt vmcnt(0)
	v_mov_b32_e32 v154, v164
	v_pk_mul_f32 v[126:127], v[126:127], v[154:155] op_sel_hi:[1,0]
	v_pk_mul_f32 v[156:157], v[116:117], v[154:155] op_sel_hi:[1,0]
	v_pk_mul_f32 v[116:117], v[114:115], v[154:155] op_sel_hi:[1,0]
	v_mul_f32_e32 v114, 0xbfb8aa3b, v126
	v_mul_f32_e32 v115, 0xbfb8aa3b, v127
	v_exp_f32_e32 v114, v114
	v_exp_f32_e32 v115, v115
	v_pk_mul_f32 v[118:119], v[118:119], v[154:155] op_sel_hi:[1,0]
	v_pk_mul_f32 v[128:129], v[128:129], v[154:155] op_sel_hi:[1,0]
	v_add_f32_e32 v114, 1.0, v114
	v_add_f32_e32 v115, 1.0, v115
	v_rcp_f32_e32 v114, v114
	v_rcp_f32_e32 v115, v115
	v_pk_mul_f32 v[120:121], v[120:121], v[154:155] op_sel_hi:[1,0]
	v_pk_mul_f32 v[122:123], v[122:123], v[154:155] op_sel_hi:[1,0]
	v_pk_mul_f32 v[124:125], v[124:125], v[154:155] op_sel_hi:[1,0]
	v_pk_mul_f32 v[114:115], v[126:127], v[114:115]
	s_nop 0
	v_pk_mul_f32 v[114:115], v[118:119], v[114:115]
	s_nop 0
	v_cvt_pk_bf16_f32 v114, v114, v115
	v_mul_f32_e32 v115, 0xbfb8aa3b, v128
	v_exp_f32_e32 v115, v115
	s_nop 0
	v_add_f32_e32 v115, 1.0, v115
	v_rcp_f32_e32 v118, v115
	v_mul_f32_e32 v115, 0xbfb8aa3b, v129
	v_exp_f32_e32 v115, v115
	s_nop 0
	v_add_f32_e32 v115, 1.0, v115
	v_rcp_f32_e32 v119, v115
	s_nop 0
	v_pk_mul_f32 v[118:119], v[128:129], v[118:119]
	s_nop 0
	v_pk_mul_f32 v[118:119], v[120:121], v[118:119]
	s_nop 0
	v_cvt_pk_bf16_f32 v115, v118, v119
	v_mul_f32_e32 v118, 0xbfb8aa3b, v122
	v_mul_f32_e32 v119, 0xbfb8aa3b, v123
	v_exp_f32_e32 v118, v118
	v_exp_f32_e32 v119, v119
	v_add_f32_e32 v118, 1.0, v118
	v_add_f32_e32 v119, 1.0, v119
	v_rcp_f32_e32 v118, v118
	v_rcp_f32_e32 v119, v119
	s_nop 0
	v_pk_mul_f32 v[118:119], v[122:123], v[118:119]
	s_nop 0
	v_pk_mul_f32 v[116:117], v[116:117], v[118:119]
	s_nop 0
	v_cvt_pk_bf16_f32 v116, v116, v117
	v_mul_f32_e32 v117, 0xbfb8aa3b, v124
	v_exp_f32_e32 v117, v117
	s_nop 0
	v_add_f32_e32 v117, 1.0, v117
	v_rcp_f32_e32 v118, v117
	v_mul_f32_e32 v117, 0xbfb8aa3b, v125
	v_exp_f32_e32 v117, v117
	s_nop 0
	v_add_f32_e32 v117, 1.0, v117
	v_rcp_f32_e32 v119, v117
	s_nop 0
	v_pk_mul_f32 v[118:119], v[124:125], v[118:119]
	s_nop 0
	v_pk_mul_f32 v[118:119], v[156:157], v[118:119]
	s_nop 0
	v_cvt_pk_bf16_f32 v117, v118, v119
	global_store_dwordx4 v[152:153], v[114:117], off
	s_nop 1
	v_or_b32_e32 v122, 16, v140
	v_ashrrev_i32_e32 v123, 31, v122
	v_mad_i64_i32 v[120:121], s[22:23], v122, s73, v[142:143]
	v_lshl_add_u64 v[122:123], v[122:123], 2, s[42:43]
	v_lshl_add_u64 v[120:121], v[120:121], 0, v[144:145]
	v_mov_b32_e32 v122, v166
	v_pk_mul_f32 v[110:111], v[110:111], v[122:123] op_sel_hi:[1,0]
	v_pk_mul_f32 v[118:119], v[100:101], v[122:123] op_sel_hi:[1,0]
	v_pk_mul_f32 v[100:101], v[98:99], v[122:123] op_sel_hi:[1,0]
	v_mul_f32_e32 v98, 0xbfb8aa3b, v110
	v_mul_f32_e32 v99, 0xbfb8aa3b, v111
	v_exp_f32_e32 v98, v98
	v_exp_f32_e32 v99, v99
	v_pk_mul_f32 v[102:103], v[102:103], v[122:123] op_sel_hi:[1,0]
	v_pk_mul_f32 v[112:113], v[112:113], v[122:123] op_sel_hi:[1,0]
	v_add_f32_e32 v98, 1.0, v98
	v_add_f32_e32 v99, 1.0, v99
	v_rcp_f32_e32 v98, v98
	v_rcp_f32_e32 v99, v99
	v_pk_mul_f32 v[104:105], v[104:105], v[122:123] op_sel_hi:[1,0]
	v_pk_mul_f32 v[106:107], v[106:107], v[122:123] op_sel_hi:[1,0]
	v_pk_mul_f32 v[108:109], v[108:109], v[122:123] op_sel_hi:[1,0]
	v_pk_mul_f32 v[98:99], v[110:111], v[98:99]
	s_nop 0
	v_pk_mul_f32 v[98:99], v[102:103], v[98:99]
	s_nop 0
	v_cvt_pk_bf16_f32 v98, v98, v99
	v_mul_f32_e32 v99, 0xbfb8aa3b, v112
	v_exp_f32_e32 v99, v99
	s_nop 0
	v_add_f32_e32 v99, 1.0, v99
	v_rcp_f32_e32 v102, v99
	v_mul_f32_e32 v99, 0xbfb8aa3b, v113
	v_exp_f32_e32 v99, v99
	s_nop 0
	v_add_f32_e32 v99, 1.0, v99
	v_rcp_f32_e32 v103, v99
	s_nop 0
	v_pk_mul_f32 v[102:103], v[112:113], v[102:103]
	s_nop 0
	v_pk_mul_f32 v[102:103], v[104:105], v[102:103]
	s_nop 0
	v_cvt_pk_bf16_f32 v99, v102, v103
	v_mul_f32_e32 v102, 0xbfb8aa3b, v106
	v_mul_f32_e32 v103, 0xbfb8aa3b, v107
	v_exp_f32_e32 v102, v102
	v_exp_f32_e32 v103, v103
	v_add_f32_e32 v102, 1.0, v102
	v_add_f32_e32 v103, 1.0, v103
	v_rcp_f32_e32 v102, v102
	v_rcp_f32_e32 v103, v103
	s_nop 0
	v_pk_mul_f32 v[102:103], v[106:107], v[102:103]
	s_nop 0
	v_pk_mul_f32 v[100:101], v[100:101], v[102:103]
	s_nop 0
	v_cvt_pk_bf16_f32 v100, v100, v101
	v_mul_f32_e32 v101, 0xbfb8aa3b, v108
	v_exp_f32_e32 v101, v101
	s_nop 0
	v_add_f32_e32 v101, 1.0, v101
	v_rcp_f32_e32 v102, v101
	v_mul_f32_e32 v101, 0xbfb8aa3b, v109
	v_exp_f32_e32 v101, v101
	s_nop 0
	v_add_f32_e32 v101, 1.0, v101
	v_rcp_f32_e32 v103, v101
	s_nop 0
	v_pk_mul_f32 v[102:103], v[108:109], v[102:103]
	s_nop 0
	v_pk_mul_f32 v[102:103], v[118:119], v[102:103]
	s_nop 0
	v_cvt_pk_bf16_f32 v101, v102, v103
	global_store_dwordx4 v[120:121], v[98:101], off
	s_nop 1
	v_or_b32_e32 v106, 32, v140
	v_ashrrev_i32_e32 v107, 31, v106
; __device__ __forceinline__ unsigned cvt_pk_bf16(float lo, float hi) { f32x2c_t v = {lo, hi}; bf16x2c_t b = __builtin_convertvector(v, bf16x2c_t); return __builtin_bit_cast(unsigned, b); }
;     __device__ __forceinline__ static float sw(float g, float u) { return g * __builtin_amdgcn_rcpf(1.f + __builtin_amdgcn_exp2f(-1.4426950408889634f * g)) * u; }
;     __device__ __forceinline__ void operator()(const f32x4 (&acc)[2][2][4][2], const Unit& u, int wr, int wc, int fr, int fq) const {
;         const int row0 = u.pm * BM + wr * 64 + fr, col0 = u.pn * HALF + wc * 32 + 8 * fq;
; #pragma unroll
;         for (int ai = 0; ai < 2; ++ai)
; #pragma unroll
;             for (int m = 0; m < 4; ++m) { bf16_t* rowp = O + (size_t)(row0 + ai * HALF + m * 16) * ldc + col0;
;                 const float r_ = rs[row0 + ai * HALF + m * 16];
;                 const f32x4 g0 = acc[ai][0][m][0] * r_, g1 = acc[ai][0][m][1] * r_, u0 = acc[ai][1][m][0] * r_, u1 = acc[ai][1][m][1] * r_;
;                 u32x4 w; w.x = cvt_pk_bf16(sw(g0[0], u0[0]), sw(g0[1], u0[1])); w.y = cvt_pk_bf16(sw(g0[2], u0[2]), sw(g0[3], u0[3]));
;                 w.z = cvt_pk_bf16(sw(g1[0], u1[0]), sw(g1[1], u1[1])); w.w = cvt_pk_bf16(sw(g1[2], u1[2]), sw(g1[3], u1[3]));
;                 *(u32x4*)rowp = w; }
	v_mad_i64_i32 v[104:105], s[22:23], v106, s73, v[142:143]
	v_lshl_add_u64 v[106:107], v[106:107], 2, s[42:43]
	v_lshl_add_u64 v[104:105], v[104:105], 0, v[144:145]
	v_mov_b32_e32 v106, v168
	v_pk_mul_f32 v[94:95], v[94:95], v[106:107] op_sel_hi:[1,0]
	v_pk_mul_f32 v[102:103], v[84:85], v[106:107] op_sel_hi:[1,0]
	v_pk_mul_f32 v[84:85], v[82:83], v[106:107] op_sel_hi:[1,0]
	v_mul_f32_e32 v82, 0xbfb8aa3b, v94
	v_mul_f32_e32 v83, 0xbfb8aa3b, v95
	v_exp_f32_e32 v82, v82
	v_exp_f32_e32 v83, v83
	v_pk_mul_f32 v[86:87], v[86:87], v[106:107] op_sel_hi:[1,0]
	v_pk_mul_f32 v[96:97], v[96:97], v[106:107] op_sel_hi:[1,0]
	v_add_f32_e32 v82, 1.0, v82
	v_add_f32_e32 v83, 1.0, v83
	v_rcp_f32_e32 v82, v82
	v_rcp_f32_e32 v83, v83
	v_pk_mul_f32 v[88:89], v[88:89], v[106:107] op_sel_hi:[1,0]
	v_pk_mul_f32 v[90:91], v[90:91], v[106:107] op_sel_hi:[1,0]
	v_pk_mul_f32 v[92:93], v[92:93], v[106:107] op_sel_hi:[1,0]
	v_pk_mul_f32 v[82:83], v[94:95], v[82:83]
	s_nop 0
	v_pk_mul_f32 v[82:83], v[86:87], v[82:83]
	s_nop 0
	v_cvt_pk_bf16_f32 v82, v82, v83
	v_mul_f32_e32 v83, 0xbfb8aa3b, v96
	v_exp_f32_e32 v83, v83
	s_nop 0
	v_add_f32_e32 v83, 1.0, v83
	v_rcp_f32_e32 v86, v83
	v_mul_f32_e32 v83, 0xbfb8aa3b, v97
	v_exp_f32_e32 v83, v83
	s_nop 0
	v_add_f32_e32 v83, 1.0, v83
	v_rcp_f32_e32 v87, v83
	s_nop 0
	v_pk_mul_f32 v[86:87], v[96:97], v[86:87]
	s_nop 0
	v_pk_mul_f32 v[86:87], v[88:89], v[86:87]
	s_nop 0
	v_cvt_pk_bf16_f32 v83, v86, v87
	v_mul_f32_e32 v86, 0xbfb8aa3b, v90
	v_mul_f32_e32 v87, 0xbfb8aa3b, v91
	v_exp_f32_e32 v86, v86
	v_exp_f32_e32 v87, v87
	v_add_f32_e32 v86, 1.0, v86
	v_add_f32_e32 v87, 1.0, v87
	v_rcp_f32_e32 v86, v86
	v_rcp_f32_e32 v87, v87
	s_nop 0
	v_pk_mul_f32 v[86:87], v[90:91], v[86:87]
	s_nop 0
	v_pk_mul_f32 v[84:85], v[84:85], v[86:87]
	s_nop 0
	v_cvt_pk_bf16_f32 v84, v84, v85
	v_mul_f32_e32 v85, 0xbfb8aa3b, v92
	v_exp_f32_e32 v85, v85
	s_nop 0
	v_add_f32_e32 v85, 1.0, v85
	v_rcp_f32_e32 v86, v85
	v_mul_f32_e32 v85, 0xbfb8aa3b, v93
	v_exp_f32_e32 v85, v85
	s_nop 0
	v_add_f32_e32 v85, 1.0, v85
	v_rcp_f32_e32 v87, v85
	s_nop 0
	v_pk_mul_f32 v[86:87], v[92:93], v[86:87]
	s_nop 0
	v_pk_mul_f32 v[86:87], v[102:103], v[86:87]
	s_nop 0
	v_cvt_pk_bf16_f32 v85, v86, v87
	global_store_dwordx4 v[104:105], v[82:85], off
	s_nop 1
	v_or_b32_e32 v90, 48, v140
	v_ashrrev_i32_e32 v91, 31, v90
	v_mad_i64_i32 v[88:89], s[22:23], v90, s73, v[142:143]
	v_lshl_add_u64 v[90:91], v[90:91], 2, s[42:43]
	v_lshl_add_u64 v[88:89], v[88:89], 0, v[144:145]
	v_mov_b32_e32 v90, v170
	v_pk_mul_f32 v[78:79], v[78:79], v[90:91] op_sel_hi:[1,0]
	v_pk_mul_f32 v[86:87], v[70:71], v[90:91] op_sel_hi:[1,0]
	v_pk_mul_f32 v[70:71], v[68:69], v[90:91] op_sel_hi:[1,0]
	v_pk_mul_f32 v[68:69], v[66:67], v[90:91] op_sel_hi:[1,0]
	v_mul_f32_e32 v66, 0xbfb8aa3b, v78
	v_mul_f32_e32 v67, 0xbfb8aa3b, v79
	v_exp_f32_e32 v66, v66
	v_exp_f32_e32 v67, v67
	v_pk_mul_f32 v[80:81], v[80:81], v[90:91] op_sel_hi:[1,0]
	v_pk_mul_f32 v[72:73], v[72:73], v[90:91] op_sel_hi:[1,0]
	v_add_f32_e32 v66, 1.0, v66
	v_add_f32_e32 v67, 1.0, v67
	v_rcp_f32_e32 v66, v66
	v_rcp_f32_e32 v67, v67
	v_pk_mul_f32 v[74:75], v[74:75], v[90:91] op_sel_hi:[1,0]
	v_pk_mul_f32 v[76:77], v[76:77], v[90:91] op_sel_hi:[1,0]
	v_pk_mul_f32 v[66:67], v[78:79], v[66:67]
	s_nop 0
	v_pk_mul_f32 v[66:67], v[86:87], v[66:67]
	s_nop 0
	v_cvt_pk_bf16_f32 v66, v66, v67
	v_mul_f32_e32 v67, 0xbfb8aa3b, v80
	v_exp_f32_e32 v67, v67
	s_nop 0
	v_add_f32_e32 v67, 1.0, v67
	v_rcp_f32_e32 v78, v67
	v_mul_f32_e32 v67, 0xbfb8aa3b, v81
	v_exp_f32_e32 v67, v67
	s_nop 0
	v_add_f32_e32 v67, 1.0, v67
	v_rcp_f32_e32 v79, v67
	s_nop 0
	v_pk_mul_f32 v[78:79], v[80:81], v[78:79]
	s_nop 0
	v_pk_mul_f32 v[72:73], v[72:73], v[78:79]
	s_nop 0
	v_cvt_pk_bf16_f32 v67, v72, v73
	v_mul_f32_e32 v72, 0xbfb8aa3b, v74
	v_mul_f32_e32 v73, 0xbfb8aa3b, v75
	v_exp_f32_e32 v72, v72
	v_exp_f32_e32 v73, v73
	v_add_f32_e32 v72, 1.0, v72
	v_add_f32_e32 v73, 1.0, v73
	v_rcp_f32_e32 v72, v72
	v_rcp_f32_e32 v73, v73
	s_nop 0
	v_pk_mul_f32 v[72:73], v[74:75], v[72:73]
	s_nop 0
	v_pk_mul_f32 v[68:69], v[68:69], v[72:73]
	s_nop 0
	v_cvt_pk_bf16_f32 v68, v68, v69
	v_mul_f32_e32 v69, 0xbfb8aa3b, v76
	v_exp_f32_e32 v69, v69
	s_nop 0
	v_add_f32_e32 v69, 1.0, v69
	v_rcp_f32_e32 v72, v69
	v_mul_f32_e32 v69, 0xbfb8aa3b, v77
	v_exp_f32_e32 v69, v69
	s_nop 0
	v_add_f32_e32 v69, 1.0, v69
	v_rcp_f32_e32 v73, v69
	s_nop 0
	v_pk_mul_f32 v[72:73], v[76:77], v[72:73]
	s_nop 0
	v_pk_mul_f32 v[70:71], v[70:71], v[72:73]
	s_nop 0
	v_cvt_pk_bf16_f32 v69, v70, v71
	global_store_dwordx4 v[88:89], v[66:69], off
	v_mov_b32_e32 v74, v172
	v_pk_mul_f32 v[62:63], v[62:63], v[74:75] op_sel_hi:[1,0]
	v_pk_mul_f32 v[70:71], v[54:55], v[74:75] op_sel_hi:[1,0]
	v_pk_mul_f32 v[54:55], v[52:53], v[74:75] op_sel_hi:[1,0]
	v_pk_mul_f32 v[52:53], v[50:51], v[74:75] op_sel_hi:[1,0]
	v_mul_f32_e32 v50, 0xbfb8aa3b, v62
	v_mul_f32_e32 v51, 0xbfb8aa3b, v63
	v_exp_f32_e32 v50, v50
	v_exp_f32_e32 v51, v51
	v_pk_mul_f32 v[64:65], v[64:65], v[74:75] op_sel_hi:[1,0]
	v_pk_mul_f32 v[56:57], v[56:57], v[74:75] op_sel_hi:[1,0]
	v_add_f32_e32 v50, 1.0, v50
	v_add_f32_e32 v51, 1.0, v51
	v_rcp_f32_e32 v50, v50
	v_rcp_f32_e32 v51, v51
	v_pk_mul_f32 v[58:59], v[58:59], v[74:75] op_sel_hi:[1,0]
	v_pk_mul_f32 v[60:61], v[60:61], v[74:75] op_sel_hi:[1,0]
	v_add_u32_e32 v72, 0x80, v140
	v_pk_mul_f32 v[50:51], v[62:63], v[50:51]
	v_mad_i64_i32 v[72:73], s[22:23], v72, s73, v[142:143]
	v_pk_mul_f32 v[50:51], v[70:71], v[50:51]
	v_lshl_add_u64 v[72:73], v[72:73], 0, v[144:145]
	v_cvt_pk_bf16_f32 v50, v50, v51
	v_mul_f32_e32 v51, 0xbfb8aa3b, v64
	v_exp_f32_e32 v51, v51
	s_nop 0
	v_add_f32_e32 v51, 1.0, v51
	v_rcp_f32_e32 v62, v51
; __device__ __forceinline__ unsigned cvt_pk_bf16(float lo, float hi) { f32x2c_t v = {lo, hi}; bf16x2c_t b = __builtin_convertvector(v, bf16x2c_t); return __builtin_bit_cast(unsigned, b); }
;     __device__ __forceinline__ static float sw(float g, float u) { return g * __builtin_amdgcn_rcpf(1.f + __builtin_amdgcn_exp2f(-1.4426950408889634f * g)) * u; }
;     __device__ __forceinline__ void operator()(const f32x4 (&acc)[2][2][4][2], const Unit& u, int wr, int wc, int fr, int fq) const {
;         const int row0 = u.pm * BM + wr * 64 + fr, col0 = u.pn * HALF + wc * 32 + 8 * fq;
; #pragma unroll
;         for (int ai = 0; ai < 2; ++ai)
; #pragma unroll
;             for (int m = 0; m < 4; ++m) { bf16_t* rowp = O + (size_t)(row0 + ai * HALF + m * 16) * ldc + col0;
;                 const float r_ = rs[row0 + ai * HALF + m * 16];
;                 const f32x4 g0 = acc[ai][0][m][0] * r_, g1 = acc[ai][0][m][1] * r_, u0 = acc[ai][1][m][0] * r_, u1 = acc[ai][1][m][1] * r_;
;                 u32x4 w; w.x = cvt_pk_bf16(sw(g0[0], u0[0]), sw(g0[1], u0[1])); w.y = cvt_pk_bf16(sw(g0[2], u0[2]), sw(g0[3], u0[3]));
;                 w.z = cvt_pk_bf16(sw(g1[0], u1[0]), sw(g1[1], u1[1])); w.w = cvt_pk_bf16(sw(g1[2], u1[2]), sw(g1[3], u1[3]));
;                 *(u32x4*)rowp = w; }
	v_mul_f32_e32 v51, 0xbfb8aa3b, v65
	v_exp_f32_e32 v51, v51
	s_nop 0
	v_add_f32_e32 v51, 1.0, v51
	v_rcp_f32_e32 v63, v51
	s_nop 0
	v_pk_mul_f32 v[62:63], v[64:65], v[62:63]
	s_nop 0
	v_pk_mul_f32 v[56:57], v[56:57], v[62:63]
	s_nop 0
	v_cvt_pk_bf16_f32 v51, v56, v57
	v_mul_f32_e32 v56, 0xbfb8aa3b, v58
	v_mul_f32_e32 v57, 0xbfb8aa3b, v59
	v_exp_f32_e32 v56, v56
	v_exp_f32_e32 v57, v57
	v_add_f32_e32 v56, 1.0, v56
	v_add_f32_e32 v57, 1.0, v57
	v_rcp_f32_e32 v56, v56
	v_rcp_f32_e32 v57, v57
	s_nop 0
	v_pk_mul_f32 v[56:57], v[58:59], v[56:57]
	s_nop 0
	v_pk_mul_f32 v[52:53], v[52:53], v[56:57]
	s_nop 0
	v_cvt_pk_bf16_f32 v52, v52, v53
	v_mul_f32_e32 v53, 0xbfb8aa3b, v60
	v_exp_f32_e32 v53, v53
	s_nop 0
	v_add_f32_e32 v53, 1.0, v53
	v_rcp_f32_e32 v56, v53
	v_mul_f32_e32 v53, 0xbfb8aa3b, v61
	v_exp_f32_e32 v53, v53
	s_nop 0
	v_add_f32_e32 v53, 1.0, v53
	v_rcp_f32_e32 v57, v53
	s_nop 0
	v_pk_mul_f32 v[56:57], v[60:61], v[56:57]
	s_nop 0
	v_pk_mul_f32 v[54:55], v[54:55], v[56:57]
	s_nop 0
	v_cvt_pk_bf16_f32 v53, v54, v55
	global_store_dwordx4 v[72:73], v[50:53], off
	v_mov_b32_e32 v58, v174
	v_pk_mul_f32 v[46:47], v[46:47], v[58:59] op_sel_hi:[1,0]
	v_pk_mul_f32 v[54:55], v[38:39], v[58:59] op_sel_hi:[1,0]
	v_pk_mul_f32 v[38:39], v[36:37], v[58:59] op_sel_hi:[1,0]
	v_pk_mul_f32 v[36:37], v[34:35], v[58:59] op_sel_hi:[1,0]
	v_mul_f32_e32 v34, 0xbfb8aa3b, v46
	v_mul_f32_e32 v35, 0xbfb8aa3b, v47
	v_exp_f32_e32 v34, v34
	v_exp_f32_e32 v35, v35
	v_pk_mul_f32 v[48:49], v[48:49], v[58:59] op_sel_hi:[1,0]
	v_pk_mul_f32 v[40:41], v[40:41], v[58:59] op_sel_hi:[1,0]
	v_add_f32_e32 v34, 1.0, v34
	v_add_f32_e32 v35, 1.0, v35
	v_rcp_f32_e32 v34, v34
	v_rcp_f32_e32 v35, v35
	v_pk_mul_f32 v[42:43], v[42:43], v[58:59] op_sel_hi:[1,0]
	v_pk_mul_f32 v[44:45], v[44:45], v[58:59] op_sel_hi:[1,0]
	v_add_u32_e32 v56, 0x90, v140
	v_pk_mul_f32 v[34:35], v[46:47], v[34:35]
	v_mad_i64_i32 v[56:57], s[22:23], v56, s73, v[142:143]
	v_pk_mul_f32 v[34:35], v[54:55], v[34:35]
	v_lshl_add_u64 v[56:57], v[56:57], 0, v[144:145]
	v_cvt_pk_bf16_f32 v34, v34, v35
	v_mul_f32_e32 v35, 0xbfb8aa3b, v48
	v_exp_f32_e32 v35, v35
	s_nop 0
	v_add_f32_e32 v35, 1.0, v35
	v_rcp_f32_e32 v46, v35
	v_mul_f32_e32 v35, 0xbfb8aa3b, v49
	v_exp_f32_e32 v35, v35
	s_nop 0
	v_add_f32_e32 v35, 1.0, v35
	v_rcp_f32_e32 v47, v35
	s_nop 0
	v_pk_mul_f32 v[46:47], v[48:49], v[46:47]
	s_nop 0
	v_pk_mul_f32 v[40:41], v[40:41], v[46:47]
	s_nop 0
	v_cvt_pk_bf16_f32 v35, v40, v41
	v_mul_f32_e32 v40, 0xbfb8aa3b, v42
	v_mul_f32_e32 v41, 0xbfb8aa3b, v43
	v_exp_f32_e32 v40, v40
	v_exp_f32_e32 v41, v41
	v_add_f32_e32 v40, 1.0, v40
	v_add_f32_e32 v41, 1.0, v41
	v_rcp_f32_e32 v40, v40
	v_rcp_f32_e32 v41, v41
	s_nop 0
	v_pk_mul_f32 v[40:41], v[42:43], v[40:41]
	s_nop 0
	v_pk_mul_f32 v[36:37], v[36:37], v[40:41]
	s_nop 0
	v_cvt_pk_bf16_f32 v36, v36, v37
	v_mul_f32_e32 v37, 0xbfb8aa3b, v44
	v_exp_f32_e32 v37, v37
	s_nop 0
	v_add_f32_e32 v37, 1.0, v37
	v_rcp_f32_e32 v40, v37
	v_mul_f32_e32 v37, 0xbfb8aa3b, v45
	v_exp_f32_e32 v37, v37
	s_nop 0
	v_add_f32_e32 v37, 1.0, v37
	v_rcp_f32_e32 v41, v37
	s_nop 0
	v_pk_mul_f32 v[40:41], v[44:45], v[40:41]
	s_nop 0
	v_pk_mul_f32 v[38:39], v[38:39], v[40:41]
	s_nop 0
	v_cvt_pk_bf16_f32 v37, v38, v39
	global_store_dwordx4 v[56:57], v[34:37], off
	v_mov_b32_e32 v42, v176
	v_pk_mul_f32 v[30:31], v[30:31], v[42:43] op_sel_hi:[1,0]
	v_pk_mul_f32 v[38:39], v[22:23], v[42:43] op_sel_hi:[1,0]
	v_pk_mul_f32 v[22:23], v[20:21], v[42:43] op_sel_hi:[1,0]
	v_pk_mul_f32 v[20:21], v[18:19], v[42:43] op_sel_hi:[1,0]
	v_mul_f32_e32 v18, 0xbfb8aa3b, v30
	v_mul_f32_e32 v19, 0xbfb8aa3b, v31
	v_exp_f32_e32 v18, v18
	v_exp_f32_e32 v19, v19
	v_pk_mul_f32 v[32:33], v[32:33], v[42:43] op_sel_hi:[1,0]
	v_pk_mul_f32 v[24:25], v[24:25], v[42:43] op_sel_hi:[1,0]
	v_add_f32_e32 v18, 1.0, v18
	v_add_f32_e32 v19, 1.0, v19
; __device__ __forceinline__ unsigned cvt_pk_bf16(float lo, float hi) { f32x2c_t v = {lo, hi}; bf16x2c_t b = __builtin_convertvector(v, bf16x2c_t); return __builtin_bit_cast(unsigned, b); }
;     __device__ __forceinline__ static float sw(float g, float u) { return g * __builtin_amdgcn_rcpf(1.f + __builtin_amdgcn_exp2f(-1.4426950408889634f * g)) * u; }
; #define PG8_BAR __builtin_amdgcn_s_barrier()
;     __device__ __forceinline__ void operator()(const f32x4 (&acc)[2][2][4][2], const Unit& u, int wr, int wc, int fr, int fq) const {
;         const int row0 = u.pm * BM + wr * 64 + fr, col0 = u.pn * HALF + wc * 32 + 8 * fq;
; #pragma unroll
;         for (int ai = 0; ai < 2; ++ai)
; #pragma unroll
;             for (int m = 0; m < 4; ++m) { bf16_t* rowp = O + (size_t)(row0 + ai * HALF + m * 16) * ldc + col0;
;                 const float r_ = rs[row0 + ai * HALF + m * 16];
;                 const f32x4 g0 = acc[ai][0][m][0] * r_, g1 = acc[ai][0][m][1] * r_, u0 = acc[ai][1][m][0] * r_, u1 = acc[ai][1][m][1] * r_;
;                 u32x4 w; w.x = cvt_pk_bf16(sw(g0[0], u0[0]), sw(g0[1], u0[1])); w.y = cvt_pk_bf16(sw(g0[2], u0[2]), sw(g0[3], u0[3]));
;                 w.z = cvt_pk_bf16(sw(g1[0], u1[0]), sw(g1[1], u1[1])); w.w = cvt_pk_bf16(sw(g1[2], u1[2]), sw(g1[3], u1[3]));
;                 *(u32x4*)rowp = w; }
; template <class Epi, class Sched, bool ALIGN_EPI = false, bool SP2 = false>
; __device__ __forceinline__ void gemm_phase(PG8_LAS unsigned char* lds, const Gemm g, const Sched& S, const Epi& E) {
;     ...
;         if constexpr (ALIGN_EPI) { if (wr == 0) PG8_BAR; }
;         if constexpr (!Epi::AFTER_DRAIN) { E(acc, cur, wr, wc, fr, fq); S.done(cur); }
;         if (!has_next) break;
; #pragma unroll
;         for (int a = 0; a < 2; ++a)
; #pragma unroll
;             for (int b = 0; b < 2; ++b)
; #pragma unroll
;                 for (int m = 0; m < 4; ++m)
; #pragma unroll
;                     for (int n = 0; n < 2; ++n) acc[a][b][m][n] = (f32x4){0.f, 0.f, 0.f, 0.f};
;         cur = nxt; cA = nA; cB = nB; ++ui;
;         if constexpr (ALIGN_EPI) { if (wr == 1) PG8_BAR; }
;     }
	v_rcp_f32_e32 v18, v18
	v_rcp_f32_e32 v19, v19
	v_pk_mul_f32 v[26:27], v[26:27], v[42:43] op_sel_hi:[1,0]
	v_pk_mul_f32 v[28:29], v[28:29], v[42:43] op_sel_hi:[1,0]
	v_add_u32_e32 v40, 0xa0, v140
	v_pk_mul_f32 v[18:19], v[30:31], v[18:19]
	v_mad_i64_i32 v[40:41], s[22:23], v40, s73, v[142:143]
	v_pk_mul_f32 v[18:19], v[38:39], v[18:19]
	v_lshl_add_u64 v[40:41], v[40:41], 0, v[144:145]
	v_cvt_pk_bf16_f32 v18, v18, v19
	v_mul_f32_e32 v19, 0xbfb8aa3b, v32
	v_exp_f32_e32 v19, v19
	s_nop 0
	v_add_f32_e32 v19, 1.0, v19
	v_rcp_f32_e32 v30, v19
	v_mul_f32_e32 v19, 0xbfb8aa3b, v33
	v_exp_f32_e32 v19, v19
	s_nop 0
	v_add_f32_e32 v19, 1.0, v19
	v_rcp_f32_e32 v31, v19
	s_nop 0
	v_pk_mul_f32 v[30:31], v[32:33], v[30:31]
	s_nop 0
	v_pk_mul_f32 v[24:25], v[24:25], v[30:31]
	s_nop 0
	v_cvt_pk_bf16_f32 v19, v24, v25
	v_mul_f32_e32 v24, 0xbfb8aa3b, v26
	v_mul_f32_e32 v25, 0xbfb8aa3b, v27
	v_exp_f32_e32 v24, v24
	v_exp_f32_e32 v25, v25
	v_add_f32_e32 v24, 1.0, v24
	v_add_f32_e32 v25, 1.0, v25
	v_rcp_f32_e32 v24, v24
	v_rcp_f32_e32 v25, v25
	s_nop 0
	v_pk_mul_f32 v[24:25], v[26:27], v[24:25]
	s_nop 0
	v_pk_mul_f32 v[20:21], v[20:21], v[24:25]
	s_nop 0
	v_cvt_pk_bf16_f32 v20, v20, v21
	v_mul_f32_e32 v21, 0xbfb8aa3b, v28
	v_exp_f32_e32 v21, v21
	s_nop 0
	v_add_f32_e32 v21, 1.0, v21
	v_rcp_f32_e32 v24, v21
	v_mul_f32_e32 v21, 0xbfb8aa3b, v29
	v_exp_f32_e32 v21, v21
	s_nop 0
	v_add_f32_e32 v21, 1.0, v21
	v_rcp_f32_e32 v25, v21
	s_nop 0
	v_pk_mul_f32 v[24:25], v[28:29], v[24:25]
	s_nop 0
	v_pk_mul_f32 v[22:23], v[22:23], v[24:25]
	s_nop 0
	v_cvt_pk_bf16_f32 v21, v22, v23
	global_store_dwordx4 v[40:41], v[18:21], off
	v_mov_b32_e32 v26, v178
	v_pk_mul_f32 v[14:15], v[14:15], v[26:27] op_sel_hi:[1,0]
	v_pk_mul_f32 v[22:23], v[4:5], v[26:27] op_sel_hi:[1,0]
	v_pk_mul_f32 v[4:5], v[2:3], v[26:27] op_sel_hi:[1,0]
	v_mul_f32_e32 v2, 0xbfb8aa3b, v14
	v_mul_f32_e32 v3, 0xbfb8aa3b, v15
	v_exp_f32_e32 v2, v2
	v_exp_f32_e32 v3, v3
	v_pk_mul_f32 v[6:7], v[6:7], v[26:27] op_sel_hi:[1,0]
	v_pk_mul_f32 v[16:17], v[16:17], v[26:27] op_sel_hi:[1,0]
	v_add_f32_e32 v2, 1.0, v2
	v_add_f32_e32 v3, 1.0, v3
	v_rcp_f32_e32 v2, v2
	v_rcp_f32_e32 v3, v3
	v_pk_mul_f32 v[8:9], v[8:9], v[26:27] op_sel_hi:[1,0]
	v_pk_mul_f32 v[10:11], v[10:11], v[26:27] op_sel_hi:[1,0]
	v_pk_mul_f32 v[12:13], v[12:13], v[26:27] op_sel_hi:[1,0]
	v_pk_mul_f32 v[2:3], v[14:15], v[2:3]
	v_add_u32_e32 v24, 0xb0, v140
	v_pk_mul_f32 v[2:3], v[6:7], v[2:3]
	v_mad_i64_i32 v[24:25], s[22:23], v24, s73, v[142:143]
	v_cvt_pk_bf16_f32 v2, v2, v3
	v_mul_f32_e32 v3, 0xbfb8aa3b, v16
	v_exp_f32_e32 v3, v3
	v_lshl_add_u64 v[24:25], v[24:25], 0, v[144:145]
	v_add_f32_e32 v3, 1.0, v3
	v_rcp_f32_e32 v6, v3
	v_mul_f32_e32 v3, 0xbfb8aa3b, v17
	v_exp_f32_e32 v3, v3
	s_nop 0
	v_add_f32_e32 v3, 1.0, v3
	v_rcp_f32_e32 v7, v3
	s_nop 0
	v_pk_mul_f32 v[6:7], v[16:17], v[6:7]
	s_nop 0
	v_pk_mul_f32 v[6:7], v[8:9], v[6:7]
	s_nop 0
	v_cvt_pk_bf16_f32 v3, v6, v7
	v_mul_f32_e32 v6, 0xbfb8aa3b, v10
	v_mul_f32_e32 v7, 0xbfb8aa3b, v11
	v_exp_f32_e32 v6, v6
	v_exp_f32_e32 v7, v7
	v_add_f32_e32 v6, 1.0, v6
	v_add_f32_e32 v7, 1.0, v7
	v_rcp_f32_e32 v6, v6
	v_rcp_f32_e32 v7, v7
	s_nop 0
	v_pk_mul_f32 v[6:7], v[10:11], v[6:7]
	s_nop 0
	v_pk_mul_f32 v[4:5], v[4:5], v[6:7]
	s_nop 0
	v_cvt_pk_bf16_f32 v4, v4, v5
	v_mul_f32_e32 v5, 0xbfb8aa3b, v12
	v_exp_f32_e32 v5, v5
	s_nop 0
	v_add_f32_e32 v5, 1.0, v5
	v_rcp_f32_e32 v6, v5
	v_mul_f32_e32 v5, 0xbfb8aa3b, v13
	v_exp_f32_e32 v5, v5
	s_nop 0
	v_add_f32_e32 v5, 1.0, v5
	v_rcp_f32_e32 v7, v5
	s_nop 0
	v_pk_mul_f32 v[6:7], v[12:13], v[6:7]
	s_nop 0
	v_pk_mul_f32 v[6:7], v[22:23], v[6:7]
	s_nop 0
	v_cvt_pk_bf16_f32 v5, v6, v7
	global_store_dwordx4 v[24:25], v[2:5], off
	s_cbranch_vccnz .LBB0_700
	s_andn2_b64 vcc, exec, s[26:27]
	s_cbranch_vccnz .LBB0_699
	s_barrier
	s_branch .LBB0_699
